# v107 + work-queue claim atomic returned into the next-index register and waited only at the next iteration (phases A, C)
# speedup vs baseline: 1.0025x; 1.0025x over previous
.LBB0_25:
	v_mov_b32_e32 v0, v176
	s_barrier
	s_nop 0
	v_cmp_eq_u32_e32 vcc, 0, v0
	s_and_saveexec_b64 s[4:5], vcc
	s_cbranch_execz .LBB0_27
	s_mov_b64 s[34:35], src_shared_base
	v_mov_b32_e32 v45, s35
	s_waitcnt vmcnt(0)
	flat_store_dword v[44:45], v100 sc0 sc1
	s_waitcnt vmcnt(0)
.LBB0_27:
	s_or_b64 exec, exec, s[4:5]
	s_waitcnt lgkmcnt(0)
	s_barrier
	flat_load_dword v6, v[46:47] sc0 sc1
	s_waitcnt vmcnt(0)
	s_movk_i32 s4, 0x413
	s_waitcnt lgkmcnt(0)
	v_cmp_gt_i32_e32 vcc, s4, v6
	s_mov_b64 s[4:5], -1
	s_and_saveexec_b64 s[34:35], vcc
	s_cbranch_execz .LBB0_24
	v_mov_b32_e32 v0, v176
	s_nop 0
	v_cmp_eq_u32_e32 vcc, 0, v0
	s_and_saveexec_b64 s[4:5], vcc
	s_cbranch_execz .LBB0_32
	s_mov_b64 s[38:39], exec
	v_mbcnt_lo_u32_b32 v0, s38, 0
	v_mbcnt_hi_u32_b32 v0, s39, v0
	v_cmp_eq_u32_e32 vcc, 0, v0
	s_and_saveexec_b64 s[36:37], vcc
	s_cbranch_execz .LBB0_31
	s_bcnt1_i32_b64 s38, s[38:39]
	v_mov_b32_e32 v1, s38
	global_atomic_add v100, v49, v1, s[68:69] sc0
.LBB0_31:
	s_or_b64 exec, exec, s[36:37]
.LBB0_32:
	s_or_b64 exec, exec, s[4:5]
	s_movk_i32 s4, 0xbf
	v_cmp_lt_i32_e32 vcc, s4, v6
	s_and_saveexec_b64 s[4:5], vcc
	s_xor_b64 s[36:37], exec, s[4:5]
	s_cbranch_execz .LBB0_74
	v_lshl_add_u32 v2, v6, 1, v99
	s_movk_i32 s4, 0x33f
	v_cmp_lt_i32_e32 vcc, s4, v2
	s_and_saveexec_b64 s[4:5], vcc
	s_xor_b64 s[38:39], exec, s[4:5]
	s_cbranch_execz .LBB0_71
	s_movk_i32 s4, 0x43f
	v_cmp_lt_u32_e32 vcc, s4, v2
	s_and_saveexec_b64 s[4:5], vcc
	s_xor_b64 s[40:41], exec, s[4:5]
	s_cbranch_execz .LBB0_68
	s_movk_i32 s4, 0x63f
	v_cmp_lt_u32_e32 vcc, s4, v2
	s_and_saveexec_b64 s[4:5], vcc
	s_xor_b64 s[42:43], exec, s[4:5]
	s_cbranch_execz .LBB0_65
	s_movk_i32 s4, 0x65f
	v_cmp_lt_u32_e32 vcc, s4, v2
	s_and_saveexec_b64 s[4:5], vcc
	s_xor_b64 s[44:45], exec, s[4:5]
	s_cbranch_execz .LBB0_62
	s_movk_i32 s4, 0x763
	v_cmp_lt_u32_e32 vcc, s4, v2
	s_and_saveexec_b64 s[4:5], vcc
	s_xor_b64 s[46:47], exec, s[4:5]
	s_cbranch_execz .LBB0_45
	s_movk_i32 s4, 0x766
	v_cmp_gt_u32_e32 vcc, s4, v2
	s_and_saveexec_b64 s[48:49], vcc
	s_cbranch_execz .LBB0_44
	v_mov_b32_e32 v0, v176
	s_movk_i32 s4, 0x764
	v_cmp_eq_u32_e32 vcc, s4, v2
	v_cmp_lt_u32_sdwa s[4:5], v0, v102 src0_sel:BYTE_0 src1_sel:DWORD
	s_and_b64 s[4:5], vcc, s[4:5]
	s_and_saveexec_b64 s[50:51], s[4:5]
	s_cbranch_execz .LBB0_42
	v_readlane_b32 s60, v250, 4
	v_lshlrev_b32_sdwa v1, v103, v0 dst_sel:DWORD dst_unused:UNUSED_PAD src0_sel:DWORD src1_sel:BYTE_0
	v_readlane_b32 s61, v250, 5
	v_readlane_b32 s62, v250, 6
	v_readlane_b32 s63, v250, 7
	v_readlane_b32 s64, v250, 8
	v_readlane_b32 s65, v250, 9
	v_readlane_b32 s66, v250, 10
	v_readlane_b32 s67, v250, 11
	global_load_dword v2, v1, s[60:61]
	global_load_dword v3, v1, s[62:63]
	s_nop 0
	global_load_dword v4, v1, s[64:65]
	s_nop 0
	global_load_dword v1, v1, s[66:67]
	v_cmp_eq_u32_sdwa s[4:5], v0, v49 src0_sel:BYTE_0 src1_sel:DWORD
	s_waitcnt vmcnt(2)
	v_mul_f32_e32 v2, v2, v3
	v_mov_b32_e32 v3, v2
	s_waitcnt vmcnt(0)
	v_mul_f32_e32 v1, v4, v1
	v_mov_b32_e32 v4, v1
	v_permlane32_swap_b32_e32 v2, v3
	s_nop 0
	v_permlane32_swap_b32_e32 v1, v4
	v_add_f32_e32 v2, v2, v3
	v_add_f32_e32 v1, v1, v4
	v_mov_b32_e32 v3, v2
	v_mov_b32_e32 v4, v1
	s_nop 0
	v_permlane16_swap_b32_e32 v2, v3
	v_permlane16_swap_b32_e32 v1, v4
	v_add_f32_e32 v2, v2, v3
	v_add_f32_e32 v1, v1, v4
	s_nop 0
	v_add_f32_dpp v2, v2, v2 row_ror:8 row_mask:0xf bank_mask:0xf bound_ctrl:1
	v_add_f32_dpp v1, v1, v1 row_ror:8 row_mask:0xf bank_mask:0xf bound_ctrl:1
	s_nop 0
	v_add_f32_dpp v2, v2, v2 row_ror:4 row_mask:0xf bank_mask:0xf bound_ctrl:1
	v_add_f32_dpp v1, v1, v1 row_ror:4 row_mask:0xf bank_mask:0xf bound_ctrl:1
	s_nop 0
	v_add_f32_dpp v3, v2, v2 quad_perm:[2,3,0,1] row_mask:0xf bank_mask:0xf bound_ctrl:1
	v_add_f32_dpp v1, v1, v1 quad_perm:[2,3,0,1] row_mask:0xf bank_mask:0xf bound_ctrl:1
	s_nop 0
	v_mov_b32_dpp v4, v3 quad_perm:[1,0,3,2] row_mask:0xf bank_mask:0xf bound_ctrl:1
	v_mov_b32_dpp v2, v1 quad_perm:[1,0,3,2] row_mask:0xf bank_mask:0xf bound_ctrl:1
	s_and_b64 exec, exec, s[4:5]
	s_cbranch_execz .LBB0_42
	v_add_f32_e32 v3, v3, v4
	v_mul_f32_e32 v4, 0x3fb8aa3b, v3
	v_fma_f32 v5, v3, s33, -v4
	v_rndne_f32_e32 v6, v4
	v_fmac_f32_e32 v5, 0x32a5705f, v3
	v_sub_f32_e32 v4, v4, v6
	v_add_f32_e32 v4, v4, v5
	v_cvt_i32_f32_e32 v5, v6
	v_exp_f32_e32 v4, v4
	v_add_f32_e32 v1, v1, v2
	v_mul_f32_e32 v2, 0x3fb8aa3b, v1
	v_rndne_f32_e32 v6, v2
	v_ldexp_f32 v4, v4, v5
	v_fma_f32 v5, v1, s33, -v2
	v_fmac_f32_e32 v5, 0x32a5705f, v1
	v_sub_f32_e32 v2, v2, v6
	v_add_f32_e32 v2, v2, v5
	v_exp_f32_e32 v2, v2
	v_cvt_i32_f32_e32 v5, v6
	v_cmp_ngt_f32_e64 s[4:5], s52, v3
	v_ldexp_f32 v2, v2, v5
	s_nop 0
	v_cndmask_b32_e64 v4, 0, v4, s[4:5]
	v_cmp_nlt_f32_e64 s[4:5], s53, v3
	s_nop 1
	v_cndmask_b32_e64 v3, v104, v4, s[4:5]
	v_cmp_ngt_f32_e64 s[4:5], s52, v1
	s_nop 1
	v_cndmask_b32_e64 v2, 0, v2, s[4:5]
	v_cmp_nlt_f32_e64 s[4:5], s53, v1
	s_nop 1
	v_cndmask_b32_e64 v1, v104, v2, s[4:5]
	v_sub_f32_e32 v1, v3, v1
	v_add_f32_e32 v1, 0x3e4ccccd, v1
	global_store_dword v49, v1, s[86:87]

.LBB0_480:
	v_mov_b32_e32 v0, v176
	s_barrier
	s_nop 0
	v_cmp_eq_u32_e32 vcc, 0, v0
	s_and_saveexec_b64 s[4:5], vcc
	s_cbranch_execz .LBB0_482
	s_mov_b64 s[6:7], src_shared_base
	v_mov_b32_e32 v163, s7
	s_waitcnt vmcnt(0)
	flat_store_dword v[162:163], v177 sc0 sc1
	s_waitcnt vmcnt(0)
.LBB0_482:
	s_or_b64 exec, exec, s[4:5]
	s_waitcnt lgkmcnt(0)
	s_barrier
	flat_load_dword v2, v[164:165] sc0 sc1
	s_waitcnt vmcnt(0)
	s_movk_i32 s4, 0x8a0
	s_waitcnt lgkmcnt(0)
	v_cmp_gt_i32_e32 vcc, s4, v2
	s_mov_b64 s[4:5], -1
	s_and_saveexec_b64 s[80:81], vcc
	s_cbranch_execz .LBB0_479
	v_mov_b32_e32 v0, v176
	s_nop 0
	v_cmp_eq_u32_e32 vcc, 0, v0
	s_and_saveexec_b64 s[4:5], vcc
	s_cbranch_execz .LBB0_487
	s_mov_b64 s[8:9], exec
	v_mbcnt_lo_u32_b32 v0, s8, 0
	v_mbcnt_hi_u32_b32 v0, s9, v0
	v_cmp_eq_u32_e32 vcc, 0, v0
	s_and_saveexec_b64 s[6:7], vcc
	s_cbranch_execz .LBB0_486
	s_bcnt1_i32_b64 s8, s[8:9]
	v_mov_b32_e32 v3, s8
	global_atomic_add v177, v1, v3, s[48:49] sc0
.LBB0_486:
	s_or_b64 exec, exec, s[6:7]
.LBB0_487:
	s_or_b64 exec, exec, s[4:5]
	s_movk_i32 s4, 0x7f
	v_cmp_lt_i32_e32 vcc, s4, v2
	s_and_saveexec_b64 s[4:5], vcc
	s_xor_b64 s[46:47], exec, s[4:5]
	s_cbranch_execz .LBB0_577
	s_movk_i32 s4, 0x47f
	v_cmp_lt_u32_e32 vcc, s4, v2
	s_and_saveexec_b64 s[4:5], vcc
	s_xor_b64 s[30:31], exec, s[4:5]
	s_cbranch_execz .LBB0_563
	v_mov_b32_e32 v40, v176
	s_movk_i32 s4, 0x1000
	v_ashrrev_i32_e32 v41, 31, v40
	v_lshlrev_b64 v[4:5], 2, v[40:41]
	v_lshl_add_u64 v[6:7], s[36:37], 0, v[4:5]
	v_add_co_u32_e32 v8, vcc, s4, v6
	s_movk_i32 s4, 0x2000
	s_nop 0
	v_addc_co_u32_e32 v9, vcc, 0, v7, vcc
	v_add_co_u32_e32 v10, vcc, s4, v6
	s_movk_i32 s4, 0x3000
	s_nop 0
	v_addc_co_u32_e32 v11, vcc, 0, v7, vcc
	v_add_co_u32_e32 v12, vcc, s4, v6
	s_movk_i32 s4, 0x4000
	s_nop 0
	v_addc_co_u32_e32 v13, vcc, 0, v7, vcc
	v_add_co_u32_e32 v14, vcc, s4, v6
	s_movk_i32 s4, 0x5000
	s_nop 0
	v_addc_co_u32_e32 v15, vcc, 0, v7, vcc
	v_add_co_u32_e32 v16, vcc, s4, v6
	s_movk_i32 s4, 0x6000
	s_nop 0
	v_addc_co_u32_e32 v17, vcc, 0, v7, vcc
	v_add_co_u32_e32 v18, vcc, s4, v6
	s_movk_i32 s4, 0x7000
	s_nop 0
	v_addc_co_u32_e32 v19, vcc, 0, v7, vcc
	global_load_dword v74, v[10:11], off offset:-4096
	global_load_dword v73, v[10:11], off
	global_load_dword v71, v[10:11], off offset:2048
	global_load_dword v70, v[14:15], off offset:-4096
	global_load_dword v69, v[14:15], off
	global_load_dword v67, v[14:15], off offset:2048
	global_load_dword v66, v[18:19], off offset:-4096
	global_load_dword v62, v[18:19], off
	v_add_co_u32_e32 v10, vcc, s4, v6
	s_mov_b32 s4, 0x8000
	s_nop 0
	v_addc_co_u32_e32 v11, vcc, 0, v7, vcc
	v_add_co_u32_e32 v14, vcc, s4, v6
	s_mov_b32 s4, 0x9000
	s_nop 0
	v_addc_co_u32_e32 v15, vcc, 0, v7, vcc
	v_add_co_u32_e32 v20, vcc, s4, v6
	s_mov_b32 s4, 0xa000
	s_nop 0
	v_addc_co_u32_e32 v21, vcc, 0, v7, vcc
	v_add_co_u32_e32 v22, vcc, s4, v6
	s_mov_b32 s4, 0xb000
	s_nop 0
	v_addc_co_u32_e32 v23, vcc, 0, v7, vcc
	v_add_co_u32_e32 v24, vcc, s4, v6
	s_mov_b32 s4, 0xc000
	s_nop 0
	v_addc_co_u32_e32 v25, vcc, 0, v7, vcc
	v_add_co_u32_e32 v26, vcc, s4, v6
	s_mov_b32 s4, 0xd000
	s_nop 0
	v_addc_co_u32_e32 v27, vcc, 0, v7, vcc
	global_load_dword v65, v[18:19], off offset:2048
	global_load_dword v64, v[14:15], off offset:-4096
	global_load_dword v61, v[14:15], off
	global_load_dword v60, v[14:15], off offset:2048
	global_load_dword v58, v[22:23], off offset:-4096
	global_load_dword v57, v[22:23], off
	global_load_dword v56, v[22:23], off offset:2048
	global_load_dword v54, v[26:27], off offset:-4096
	global_load_dword v77, v[6:7], off
	global_load_dword v76, v[6:7], off offset:2048
	global_load_dword v75, v[8:9], off offset:2048
	global_load_dword v72, v[12:13], off offset:2048
	global_load_dword v68, v[16:17], off offset:2048
	global_load_dword v63, v[10:11], off offset:2048
	global_load_dword v59, v[20:21], off offset:2048
	global_load_dword v55, v[24:25], off offset:2048
	v_add_co_u32_e32 v8, vcc, s4, v6
	s_mov_b32 s4, 0xe000
	s_nop 0
	v_addc_co_u32_e32 v9, vcc, 0, v7, vcc
	v_add_co_u32_e32 v10, vcc, s4, v6
	s_mov_b32 s4, 0xf000
	s_nop 0
	v_addc_co_u32_e32 v11, vcc, 0, v7, vcc
	global_load_dword v53, v[26:27], off
	global_load_dword v51, v[26:27], off offset:2048
	global_load_dword v50, v[10:11], off offset:-4096
	global_load_dword v48, v[10:11], off
	global_load_dword v41, v[10:11], off offset:2048
	v_add_co_u32_e32 v6, vcc, s4, v6
	v_lshl_add_u64 v[4:5], s[38:39], 0, v[4:5]
	s_nop 0
	v_addc_co_u32_e32 v7, vcc, 0, v7, vcc
	global_load_dword v52, v[8:9], off offset:2048
	global_load_dword v49, v[6:7], off
	global_load_dword v37, v[4:5], off
	v_add_u32_e32 v3, 0xfffffb80, v2
	s_movk_i32 s4, 0x3ff
	v_add_u32_e32 v0, 0xfffff780, v2
	v_lshrrev_b32_e32 v2, 6, v3
	v_cmp_lt_u32_e64 s[4:5], s4, v3
	v_lshlrev_b32_e32 v3, 5, v3
	v_and_b32_e32 v3, 0x7e0, v3
	v_cndmask_b32_e64 v6, v2, v0, s[4:5]
	v_lshlrev_b64 v[4:5], 5, v[0:1]
	v_mul_lo_u32 v0, v6, 30
	v_lshlrev_b32_e32 v78, 3, v40
	v_lshlrev_b32_e32 v8, 11, v2
	v_lshlrev_b64 v[6:7], 11, v[0:1]
	v_cndmask_b32_e64 v36, v3, 0, s[4:5]
	v_lshl_add_u64 v[4:5], v[4:5], 0, s[64:65]
	v_and_b32_e32 v3, 0x1f8, v78
	v_cndmask_b32_e64 v39, 0, v5, s[4:5]
	v_cndmask_b32_e64 v38, v8, v4, s[4:5]
	v_lshl_add_u64 v[4:5], s[22:23], 0, v[6:7]
	v_lshlrev_b32_e32 v0, 2, v3
	v_lshlrev_b32_e32 v34, 1, v3
	v_mov_b32_e32 v35, v1
	s_movk_i32 s6, 0xf80
	v_mov_b32_e32 v2, 0
	v_subrev_u32_e32 v46, 30, v36
	v_lshl_add_u64 v[44:45], v[4:5], 0, v[0:1]
	v_lshl_add_u64 v[42:43], s[50:51], 0, v[34:35]
	v_ashrrev_i32_e32 v35, 6, v40
	v_cmp_gt_i32_e32 vcc, s6, v40
	v_mov_b32_e32 v6, 0
	v_mov_b32_e32 v7, 0
	v_mov_b32_e32 v8, 0
	v_mov_b32_e32 v9, 0
	s_and_saveexec_b64 s[8:9], vcc
	s_cbranch_execz .LBB0_497
	v_add_u32_e32 v4, v35, v46
	v_cmp_gt_i32_e64 s[6:7], 0, v4
	s_and_saveexec_b64 s[10:11], s[6:7]
	s_xor_b64 s[6:7], exec, s[10:11]
	s_cbranch_execz .LBB0_494
	v_mov_b32_e32 v9, 0
	v_mov_b32_e32 v8, 0
	v_mov_b32_e32 v7, 0
	v_mov_b32_e32 v6, 0
	s_and_saveexec_b64 s[10:11], s[4:5]
	s_cbranch_execz .LBB0_493
	v_lshlrev_b32_e32 v4, 9, v35
	v_ashrrev_i32_e32 v5, 31, v4
	v_lshl_add_u64 v[8:9], v[4:5], 2, v[44:45]
	global_load_dwordx4 v[4:7], v[8:9], off
	s_nop 0
	global_load_dwordx4 v[8:11], v[8:9], off offset:16
	s_waitcnt vmcnt(1)
	v_bfe_u32 v3, v4, 16, 1
	v_bfe_u32 v12, v5, 16, 1
	v_bfe_u32 v13, v6, 16, 1
	s_waitcnt vmcnt(0)
	v_bfe_u32 v15, v8, 16, 1
	v_bfe_u32 v16, v9, 16, 1
	v_bfe_u32 v17, v10, 16, 1
	v_bfe_u32 v14, v7, 16, 1
	v_bfe_u32 v18, v11, 16, 1
	v_add3_u32 v3, v4, v3, s67
	v_add3_u32 v4, v5, v12, s67
	v_add3_u32 v5, v6, v13, s67
	v_add3_u32 v6, v8, v15, s67
	v_add3_u32 v8, v9, v16, s67
	v_add3_u32 v9, v10, v17, s67
	v_add3_u32 v7, v7, v14, s67
	v_add3_u32 v10, v11, v18, s67
	v_lshrrev_b32_e32 v3, 16, v3
	v_lshrrev_b32_e32 v5, 16, v5
	v_lshrrev_b32_e32 v11, 16, v6
	v_lshrrev_b32_e32 v9, 16, v9
	v_and_or_b32 v6, v4, s89, v3
	v_and_or_b32 v7, v7, s89, v5
	v_and_or_b32 v8, v8, s89, v11
	v_and_or_b32 v9, v10, s89, v9
